# prologue w_in transpose: tile order k-fastest so that concurrently running workgroups write whole contiguous destination rows (better DRAM write locality)
# speedup vs baseline: 1.0048x; 1.0048x over previous
; DEV int tid_() { int t = threadIdx.x; asm volatile("" : "+v"(t)); return t; }
; DEV int bid_() { int t = blockIdx.x; asm volatile("" : "+s"(t)); return t; }
; DEV int gdim_() { int t = gridDim.x; asm volatile("" : "+s"(t)); return t; }
; __device__ void transpose_convert(const float* __restrict__ src, int K, int N, u16* __restrict__ dst, char* smem) {
;   float* tile = (float*)smem;
;   const int tilesN = N >> 6, ntiles = (K >> 6) * tilesN;
;   const int tid = tid_();
;   for (int t = bid_(); t < ntiles; t += gdim_()) {
;     const int k0 = (t / tilesN) << 6, n0 = (t % tilesN) << 6;
;     __syncthreads();
;     const int ty = tid >> 4, tx = tid & 15;
; #pragma unroll
;     for (int pp = 0; pp < 4; ++pp) {
;       int k = ty + 16 * pp;
;       float4 v = *(const float4*)(src + (size_t)(k0 + k) * N + n0 + tx * 4);
;       float* d = tile + k * 65 + tx * 4;
;       d[0] = v.x; d[1] = v.y; d[2] = v.z; d[3] = v.w;
;     }
;     __syncthreads();
;     const int n = tid >> 2, ks = (tid & 3) * 16;
;     unsigned o[8];
; #pragma unroll
;     for (int e = 0; e < 8; ++e) o[e] = pack2(tile[(ks + 2 * e) * 65 + n], tile[(ks + 2 * e + 1) * 65 + n]);
;     uint4* d = (uint4*)(dst + (size_t)(n0 + n) * K + k0 + ks);
;     d[0] = make_uint4(o[0], o[1], o[2], o[3]);
;     d[1] = make_uint4(o[4], o[5], o[6], o[7]);
;   }
.LBB0_22:
	s_and_b32 s6, s0, 31
	s_lshl_b32 s6, s6, 6
	s_lshr_b32 s8, s0, 5
	s_lshl_b32 s8, s8, 6
	s_ashr_i32 s9, s8, 31
	v_add_u32_e32 v21, s6, v8
	v_lshl_add_u64 v[22:23], s[8:9], 2, v[6:7]
	v_add_u32_e32 v24, 16, v21
	v_add_u32_e32 v25, 32, v21
	v_add_u32_e32 v26, 48, v21
	v_mad_i64_i32 v[38:39], s[12:13], v21, s1, v[22:23]
	s_waitcnt lgkmcnt(0)
	s_barrier
	v_mad_i64_i32 v[40:41], s[12:13], v24, s1, v[22:23]
	v_mad_i64_i32 v[42:43], s[12:13], v25, s1, v[22:23]
	v_mad_i64_i32 v[44:45], s[12:13], v26, s1, v[22:23]
	flat_load_dwordx4 v[22:25], v[38:39]
	flat_load_dwordx4 v[26:29], v[40:41]
	flat_load_dwordx4 v[30:33], v[42:43]
	flat_load_dwordx4 v[34:37], v[44:45]
	v_add_u32_e32 v38, s8, v9
	v_ashrrev_i32_e32 v39, 31, v38
	v_lshlrev_b64 v[38:39], 12, v[38:39]
	s_ashr_i32 s7, s6, 31
	v_lshl_add_u64 v[38:39], v[2:3], 0, v[38:39]
	v_lshl_add_u64 v[38:39], s[6:7], 1, v[38:39]
	s_mov_b32 s9, s34
	v_lshl_add_u64 v[38:39], v[38:39], 0, v[4:5]
	s_waitcnt vmcnt(0) lgkmcnt(0)
	ds_write2_b32 v11, v22, v23 offset1:1
	ds_write2_b32 v11, v24, v25 offset0:2 offset1:3
	ds_write2_b32 v12, v26, v27 offset1:1
	ds_write2_b32 v13, v28, v29 offset1:1
	ds_write2_b32 v14, v30, v31 offset1:1
	ds_write2_b32 v15, v32, v33 offset1:1
	ds_write2_b32 v16, v34, v35 offset1:1
	ds_write2_b32 v17, v36, v37 offset1:1
	s_waitcnt lgkmcnt(0)
	s_barrier
	ds_read2_b32 v[22:23], v10 offset1:65
	ds_read2_b32 v[24:25], v10 offset0:130 offset1:195
	ds_read2_b32 v[26:27], v18 offset0:4 offset1:69
	ds_read2_b32 v[28:29], v18 offset0:134 offset1:199
	ds_read2_b32 v[30:31], v19 offset0:8 offset1:73
	ds_read2_b32 v[32:33], v19 offset0:138 offset1:203
	ds_read2_b32 v[34:35], v20 offset0:12 offset1:77
	ds_read2_b32 v[36:37], v20 offset0:142 offset1:207
	s_waitcnt lgkmcnt(7)
	v_cvt_pk_bf16_f32 v22, v22, v23
	s_waitcnt lgkmcnt(6)
	v_cvt_pk_bf16_f32 v23, v24, v25
	s_waitcnt lgkmcnt(5)
	v_cvt_pk_bf16_f32 v24, v26, v27
	s_waitcnt lgkmcnt(4)
	v_cvt_pk_bf16_f32 v25, v28, v29
	s_waitcnt lgkmcnt(3)
	v_cvt_pk_bf16_f32 v26, v30, v31
	s_waitcnt lgkmcnt(2)
	v_cvt_pk_bf16_f32 v27, v32, v33
	s_waitcnt lgkmcnt(1)
	v_cvt_pk_bf16_f32 v28, v34, v35
	s_waitcnt lgkmcnt(0)
	v_cvt_pk_bf16_f32 v29, v36, v37
	flat_store_dwordx4 v[38:39], v[22:25]
	flat_store_dwordx4 v[38:39], v[26:29] offset:16
	s_add_i32 s0, s9, s0
	s_cmpk_lt_i32 s0, 0x2600
	s_cbranch_scc1 .LBB0_22
